# P0 weight transpose: 32 per-k gain loads of each item issued together (was 8 serialized groups of 4 with waits)
# baseline (speedup 1.0000x reference)
.LBB0_4:
	s_mul_hi_i32 s4, s10, 0x5397829d
	s_lshr_b32 s5, s4, 31
	s_ashr_i32 s4, s4, 5
	s_add_i32 s5, s4, s5
	s_lshl_b32 s4, s5, 6
	s_mulk_i32 s5, 0xf3c0
	s_add_i32 s6, s11, s5
	v_or_b32_e32 v6, s4, v8
	s_ashr_i32 s7, s6, 31
	v_lshl_add_u64 v[16:17], s[6:7], 2, v[2:3]
	v_add_u32_e32 v7, 2, v6
	v_mad_i64_i32 v[20:21], s[8:9], v7, s16, v[16:17]
	v_or_b32_e32 v7, 4, v6
	v_mad_i64_i32 v[22:23], s[8:9], v7, s16, v[16:17]
	v_add_u32_e32 v7, 6, v6
	v_mad_i64_i32 v[24:25], s[8:9], v7, s16, v[16:17]
	v_or_b32_e32 v7, 8, v6
	v_mad_i64_i32 v[26:27], s[8:9], v7, s16, v[16:17]
	v_add_u32_e32 v7, 10, v6
	v_mad_i64_i32 v[28:29], s[8:9], v7, s16, v[16:17]
	v_or_b32_e32 v7, 12, v6
	v_mad_i64_i32 v[30:31], s[8:9], v7, s16, v[16:17]
	v_add_u32_e32 v7, 14, v6
	v_mad_i64_i32 v[18:19], s[8:9], v6, s16, v[16:17]
	v_mad_i64_i32 v[32:33], s[8:9], v7, s16, v[16:17]
	v_or_b32_e32 v7, 16, v6
	global_load_dword v45, v[18:19], off nt
	global_load_dword v47, v[20:21], off nt
	global_load_dword v46, v[22:23], off nt
	global_load_dword v44, v[24:25], off nt
	global_load_dword v41, v[26:27], off nt
	global_load_dword v43, v[28:29], off nt
	global_load_dword v42, v[30:31], off nt
	global_load_dword v40, v[32:33], off nt
	v_mad_i64_i32 v[18:19], s[8:9], v7, s16, v[16:17]
	v_add_u32_e32 v7, 18, v6
	v_mad_i64_i32 v[20:21], s[8:9], v7, s16, v[16:17]
	v_or_b32_e32 v7, 20, v6
	v_mad_i64_i32 v[22:23], s[8:9], v7, s16, v[16:17]
	v_add_u32_e32 v7, 22, v6
	v_mad_i64_i32 v[24:25], s[8:9], v7, s16, v[16:17]
	v_or_b32_e32 v7, 24, v6
	v_mad_i64_i32 v[26:27], s[8:9], v7, s16, v[16:17]
	v_add_u32_e32 v7, 26, v6
	v_mad_i64_i32 v[28:29], s[8:9], v7, s16, v[16:17]
	v_or_b32_e32 v7, 28, v6
	v_mad_i64_i32 v[30:31], s[8:9], v7, s16, v[16:17]
	v_add_u32_e32 v7, 30, v6
	v_mad_i64_i32 v[48:49], s[8:9], v7, s16, v[16:17]
	v_or_b32_e32 v7, 32, v6
	global_load_dword v37, v[18:19], off nt
	global_load_dword v39, v[20:21], off nt
	global_load_dword v38, v[22:23], off nt
	global_load_dword v36, v[24:25], off nt
	global_load_dword v33, v[26:27], off nt
	global_load_dword v35, v[28:29], off nt
	global_load_dword v34, v[30:31], off nt
	global_load_dword v32, v[48:49], off nt
	v_mad_i64_i32 v[18:19], s[8:9], v7, s16, v[16:17]
	v_add_u32_e32 v7, 34, v6
	v_mad_i64_i32 v[20:21], s[8:9], v7, s16, v[16:17]
	v_or_b32_e32 v7, 36, v6
	v_mad_i64_i32 v[22:23], s[8:9], v7, s16, v[16:17]
	v_add_u32_e32 v7, 38, v6
	v_mad_i64_i32 v[24:25], s[8:9], v7, s16, v[16:17]
	v_or_b32_e32 v7, 40, v6
	v_mad_i64_i32 v[26:27], s[8:9], v7, s16, v[16:17]
	v_add_u32_e32 v7, 42, v6
	v_mad_i64_i32 v[48:49], s[8:9], v7, s16, v[16:17]
	v_or_b32_e32 v7, 44, v6
	v_mad_i64_i32 v[50:51], s[8:9], v7, s16, v[16:17]
	v_add_u32_e32 v7, 46, v6
	v_mad_i64_i32 v[52:53], s[8:9], v7, s16, v[16:17]
	v_or_b32_e32 v7, 48, v6
	global_load_dword v29, v[18:19], off nt
	global_load_dword v31, v[20:21], off nt
	global_load_dword v30, v[22:23], off nt
	global_load_dword v28, v[24:25], off nt
	s_nop 0
	global_load_dword v25, v[26:27], off nt
	s_nop 0
	global_load_dword v27, v[48:49], off nt
	global_load_dword v26, v[50:51], off nt
	global_load_dword v24, v[52:53], off nt
	v_mad_i64_i32 v[18:19], s[8:9], v7, s16, v[16:17]
	v_add_u32_e32 v7, 50, v6
	v_mad_i64_i32 v[22:23], s[8:9], v7, s16, v[16:17]
	v_or_b32_e32 v7, 52, v6
	v_mad_i64_i32 v[48:49], s[8:9], v7, s16, v[16:17]
	v_add_u32_e32 v7, 54, v6
	v_mad_i64_i32 v[50:51], s[8:9], v7, s16, v[16:17]
	v_or_b32_e32 v7, 56, v6
	v_mad_i64_i32 v[52:53], s[8:9], v7, s16, v[16:17]
	v_add_u32_e32 v7, 58, v6
	v_mad_i64_i32 v[54:55], s[8:9], v7, s16, v[16:17]
	v_or_b32_e32 v7, 60, v6
	v_mad_i64_i32 v[56:57], s[8:9], v7, s16, v[16:17]
	v_add_u32_e32 v7, 62, v6
	v_mad_i64_i32 v[58:59], s[8:9], v7, s16, v[16:17]
	global_load_dword v21, v[18:19], off nt
	s_nop 0
	global_load_dword v23, v[22:23], off nt
	s_nop 0
	global_load_dword v22, v[48:49], off nt
	global_load_dword v20, v[50:51], off nt
	global_load_dword v17, v[52:53], off nt
	global_load_dword v19, v[54:55], off nt
	global_load_dword v18, v[56:57], off nt
	global_load_dword v16, v[58:59], off nt
	v_ashrrev_i32_e32 v7, 31, v6
	s_and_b64 vcc, exec, s[0:1]
	v_lshl_add_u64 v[6:7], v[6:7], 2, s[50:51]
	s_cbranch_vccnz .LBB0_27
	global_load_dword v100, v[6:7], off
	global_load_dword v101, v[6:7], off offset:8
	global_load_dword v102, v[6:7], off offset:16
	global_load_dword v103, v[6:7], off offset:24
	global_load_dword v104, v[6:7], off offset:32
	global_load_dword v105, v[6:7], off offset:40
	global_load_dword v106, v[6:7], off offset:48
	global_load_dword v107, v[6:7], off offset:56
	global_load_dword v108, v[6:7], off offset:64
	global_load_dword v109, v[6:7], off offset:72
	global_load_dword v110, v[6:7], off offset:80
	global_load_dword v111, v[6:7], off offset:88
	global_load_dword v112, v[6:7], off offset:96
	global_load_dword v113, v[6:7], off offset:104
	global_load_dword v114, v[6:7], off offset:112
	global_load_dword v115, v[6:7], off offset:120
	global_load_dword v116, v[6:7], off offset:128
	global_load_dword v117, v[6:7], off offset:136
	global_load_dword v118, v[6:7], off offset:144
	global_load_dword v119, v[6:7], off offset:152
	global_load_dword v120, v[6:7], off offset:160
	global_load_dword v121, v[6:7], off offset:168
	global_load_dword v122, v[6:7], off offset:176
	global_load_dword v123, v[6:7], off offset:184
	global_load_dword v124, v[6:7], off offset:192
	global_load_dword v125, v[6:7], off offset:200
	global_load_dword v126, v[6:7], off offset:208
	global_load_dword v127, v[6:7], off offset:216
	global_load_dword v128, v[6:7], off offset:224
	global_load_dword v129, v[6:7], off offset:232
	global_load_dword v130, v[6:7], off offset:240
	global_load_dword v131, v[6:7], off offset:248
	s_waitcnt vmcnt(0)
	v_mov_b32_e32 v49, v100
	v_mov_b32_e32 v50, v101
	v_mov_b32_e32 v51, v102
	v_mov_b32_e32 v48, v103
	s_waitcnt vmcnt(3)
	v_mul_f32_e32 v52, v45, v49
	s_waitcnt vmcnt(2)
	v_mul_f32_e32 v50, v47, v50
	s_waitcnt vmcnt(1)
	v_mul_f32_e32 v49, v46, v51
	ds_write2_b32 v11, v52, v50 offset1:66
	s_cbranch_execnz .LBB0_7

.LBB0_7:
	s_waitcnt vmcnt(0)
	v_mul_f32_e32 v44, v44, v48
	s_and_b64 vcc, exec, s[0:1]
	ds_write2_b32 v12, v49, v44 offset1:66
	s_cbranch_vccnz .LBB0_28
	v_mov_b32_e32 v45, v104
	v_mov_b32_e32 v46, v105
	v_mov_b32_e32 v47, v106
	v_mov_b32_e32 v44, v107
	s_waitcnt vmcnt(3)
	v_mul_f32_e32 v48, v41, v45
	s_waitcnt vmcnt(2)
	v_mul_f32_e32 v46, v43, v46
	s_waitcnt vmcnt(1)
	v_mul_f32_e32 v45, v42, v47
	ds_write2_b32 v14, v48, v46 offset1:66
	s_cbranch_execnz .LBB0_10

.LBB0_10:
	s_waitcnt vmcnt(0)
	v_mul_f32_e32 v40, v40, v44
	s_and_b64 vcc, exec, s[0:1]
	ds_write2_b32 v13, v45, v40 offset1:66
	s_cbranch_vccnz .LBB0_29
	v_mov_b32_e32 v41, v108
	v_mov_b32_e32 v42, v109
	v_mov_b32_e32 v43, v110
	v_mov_b32_e32 v40, v111
	s_waitcnt vmcnt(3)
	v_mul_f32_e32 v44, v37, v41
	s_waitcnt vmcnt(2)
	v_mul_f32_e32 v42, v39, v42
	s_waitcnt vmcnt(1)
	v_mul_f32_e32 v41, v38, v43
	ds_write2_b32 v15, v44, v42 offset1:66
	s_cbranch_execnz .LBB0_13

.LBB0_13:
	s_waitcnt vmcnt(0)
	v_mul_f32_e32 v36, v36, v40
	ds_write2_b32 v15, v41, v36 offset0:132 offset1:198
	s_and_b64 vcc, exec, s[0:1]
	v_add_u32_e32 v36, 0x400, v15
	s_cbranch_vccnz .LBB0_30
	v_mov_b32_e32 v38, v112
	v_mov_b32_e32 v39, v113
	v_mov_b32_e32 v40, v114
	v_mov_b32_e32 v37, v115
	s_waitcnt vmcnt(3)
	v_mul_f32_e32 v41, v33, v38
	s_waitcnt vmcnt(2)
	v_mul_f32_e32 v39, v35, v39
	s_waitcnt vmcnt(1)
	v_mul_f32_e32 v38, v34, v40
	ds_write2_b32 v36, v41, v39 offset0:8 offset1:74
	s_cbranch_execnz .LBB0_16

.LBB0_16:
	s_waitcnt vmcnt(0)
	v_mul_f32_e32 v32, v32, v37
	ds_write2_b32 v36, v38, v32 offset0:140 offset1:206
	s_and_b64 vcc, exec, s[0:1]
	v_add_u32_e32 v32, 0x800, v15
	s_cbranch_vccnz .LBB0_31
	v_mov_b32_e32 v34, v116
	v_mov_b32_e32 v35, v117
	v_mov_b32_e32 v36, v118
	v_mov_b32_e32 v33, v119
	s_waitcnt vmcnt(3)
	v_mul_f32_e32 v37, v29, v34
	s_waitcnt vmcnt(2)
	v_mul_f32_e32 v35, v31, v35
	s_waitcnt vmcnt(1)
	v_mul_f32_e32 v34, v30, v36
	ds_write2_b32 v32, v37, v35 offset0:16 offset1:82
	s_cbranch_execnz .LBB0_19

.LBB0_19:
	s_waitcnt vmcnt(0)
	v_mul_f32_e32 v28, v28, v33
	ds_write2_b32 v32, v34, v28 offset0:148 offset1:214
	s_and_b64 vcc, exec, s[0:1]
	v_add_u32_e32 v28, 0xc00, v15
	s_cbranch_vccnz .LBB0_32
	v_mov_b32_e32 v30, v120
	v_mov_b32_e32 v31, v121
	v_mov_b32_e32 v32, v122
	v_mov_b32_e32 v29, v123
	s_waitcnt vmcnt(3)
	v_mul_f32_e32 v33, v25, v30
	s_waitcnt vmcnt(2)
	v_mul_f32_e32 v31, v27, v31
	s_waitcnt vmcnt(1)
	v_mul_f32_e32 v30, v26, v32
	ds_write2_b32 v28, v33, v31 offset0:24 offset1:90
	s_cbranch_execnz .LBB0_22

.LBB0_22:
	s_waitcnt vmcnt(0)
	v_mul_f32_e32 v24, v24, v29
	ds_write2_b32 v28, v30, v24 offset0:156 offset1:222
	s_and_b64 vcc, exec, s[0:1]
	v_add_u32_e32 v24, 0x1000, v15
	s_cbranch_vccnz .LBB0_33
	v_mov_b32_e32 v26, v124
	v_mov_b32_e32 v27, v125
	v_mov_b32_e32 v28, v126
	v_mov_b32_e32 v25, v127
	s_waitcnt vmcnt(3)
	v_mul_f32_e32 v29, v21, v26
	s_waitcnt vmcnt(2)
	v_mul_f32_e32 v27, v23, v27
	s_waitcnt vmcnt(1)
	v_mul_f32_e32 v26, v22, v28
	ds_write2_b32 v24, v29, v27 offset0:32 offset1:98
	s_cbranch_execnz .LBB0_25

.LBB0_25:
	s_waitcnt vmcnt(0)
	v_mul_f32_e32 v20, v20, v25
	ds_write2_b32 v24, v26, v20 offset0:164 offset1:230
	s_and_b64 vcc, exec, s[0:1]
	v_add_u32_e32 v20, 0x1400, v15
	s_cbranch_vccnz .LBB0_34
	v_mov_b32_e32 v21, v128
	v_mov_b32_e32 v22, v129
	v_mov_b32_e32 v23, v130
	s_nop 0
	v_mov_b32_e32 v6, v131
	s_waitcnt vmcnt(3)
	v_mul_f32_e32 v21, v17, v21
	s_waitcnt vmcnt(2)
	v_mul_f32_e32 v22, v19, v22
	s_waitcnt vmcnt(1)
	v_mul_f32_e32 v7, v18, v23
	ds_write2_b32 v20, v21, v22 offset0:40 offset1:106
	s_cbranch_execnz .LBB0_3
	s_branch .LBB0_35

.LBB0_39:
	s_mul_hi_i32 s4, s10, 0x2aaaaaab
	s_lshr_b32 s5, s4, 31
	s_ashr_i32 s4, s4, 4
	s_add_i32 s5, s4, s5
	s_lshl_b32 s4, s5, 6
	s_mulk_i32 s5, 0xf400
	s_add_i32 s6, s11, s5
	v_or_b32_e32 v6, s4, v8
	s_ashr_i32 s7, s6, 31
	v_lshl_add_u64 v[16:17], s[6:7], 2, v[2:3]
	v_add_u32_e32 v7, 2, v6
	v_mad_i64_i32 v[20:21], s[8:9], v7, s16, v[16:17]
	v_or_b32_e32 v7, 4, v6
	v_mad_i64_i32 v[22:23], s[8:9], v7, s16, v[16:17]
	v_add_u32_e32 v7, 6, v6
	v_mad_i64_i32 v[24:25], s[8:9], v7, s16, v[16:17]
	v_or_b32_e32 v7, 8, v6
	v_mad_i64_i32 v[26:27], s[8:9], v7, s16, v[16:17]
	v_add_u32_e32 v7, 10, v6
	v_mad_i64_i32 v[28:29], s[8:9], v7, s16, v[16:17]
	v_or_b32_e32 v7, 12, v6
	v_mad_i64_i32 v[30:31], s[8:9], v7, s16, v[16:17]
	v_add_u32_e32 v7, 14, v6
	v_mad_i64_i32 v[18:19], s[8:9], v6, s16, v[16:17]
	v_mad_i64_i32 v[32:33], s[8:9], v7, s16, v[16:17]
	v_or_b32_e32 v7, 16, v6
	global_load_dword v45, v[18:19], off nt
	global_load_dword v47, v[20:21], off nt
	global_load_dword v46, v[22:23], off nt
	global_load_dword v44, v[24:25], off nt
	global_load_dword v41, v[26:27], off nt
	global_load_dword v43, v[28:29], off nt
	global_load_dword v42, v[30:31], off nt
	global_load_dword v40, v[32:33], off nt
	v_mad_i64_i32 v[18:19], s[8:9], v7, s16, v[16:17]
	v_add_u32_e32 v7, 18, v6
	v_mad_i64_i32 v[20:21], s[8:9], v7, s16, v[16:17]
	v_or_b32_e32 v7, 20, v6
	v_mad_i64_i32 v[22:23], s[8:9], v7, s16, v[16:17]
	v_add_u32_e32 v7, 22, v6
	v_mad_i64_i32 v[24:25], s[8:9], v7, s16, v[16:17]
	v_or_b32_e32 v7, 24, v6
	v_mad_i64_i32 v[26:27], s[8:9], v7, s16, v[16:17]
	v_add_u32_e32 v7, 26, v6
	v_mad_i64_i32 v[28:29], s[8:9], v7, s16, v[16:17]
	v_or_b32_e32 v7, 28, v6
	v_mad_i64_i32 v[30:31], s[8:9], v7, s16, v[16:17]
	v_add_u32_e32 v7, 30, v6
	v_mad_i64_i32 v[48:49], s[8:9], v7, s16, v[16:17]
	v_or_b32_e32 v7, 32, v6
	global_load_dword v37, v[18:19], off nt
	global_load_dword v39, v[20:21], off nt
	global_load_dword v38, v[22:23], off nt
	global_load_dword v36, v[24:25], off nt
	global_load_dword v33, v[26:27], off nt
	global_load_dword v35, v[28:29], off nt
	global_load_dword v34, v[30:31], off nt
	global_load_dword v32, v[48:49], off nt
	v_mad_i64_i32 v[18:19], s[8:9], v7, s16, v[16:17]
	v_add_u32_e32 v7, 34, v6
	v_mad_i64_i32 v[20:21], s[8:9], v7, s16, v[16:17]
	v_or_b32_e32 v7, 36, v6
	v_mad_i64_i32 v[22:23], s[8:9], v7, s16, v[16:17]
	v_add_u32_e32 v7, 38, v6
	v_mad_i64_i32 v[24:25], s[8:9], v7, s16, v[16:17]
	v_or_b32_e32 v7, 40, v6
	v_mad_i64_i32 v[26:27], s[8:9], v7, s16, v[16:17]
	v_add_u32_e32 v7, 42, v6
	v_mad_i64_i32 v[48:49], s[8:9], v7, s16, v[16:17]
	v_or_b32_e32 v7, 44, v6
	v_mad_i64_i32 v[50:51], s[8:9], v7, s16, v[16:17]
	v_add_u32_e32 v7, 46, v6
	v_mad_i64_i32 v[52:53], s[8:9], v7, s16, v[16:17]
	v_or_b32_e32 v7, 48, v6
	global_load_dword v29, v[18:19], off nt
	global_load_dword v31, v[20:21], off nt
	global_load_dword v30, v[22:23], off nt
	global_load_dword v28, v[24:25], off nt
	s_nop 0
	global_load_dword v25, v[26:27], off nt
	s_nop 0
	global_load_dword v27, v[48:49], off nt
	global_load_dword v26, v[50:51], off nt
	global_load_dword v24, v[52:53], off nt
	v_mad_i64_i32 v[18:19], s[8:9], v7, s16, v[16:17]
	v_add_u32_e32 v7, 50, v6
	v_mad_i64_i32 v[22:23], s[8:9], v7, s16, v[16:17]
	v_or_b32_e32 v7, 52, v6
	v_mad_i64_i32 v[48:49], s[8:9], v7, s16, v[16:17]
	v_add_u32_e32 v7, 54, v6
	v_mad_i64_i32 v[50:51], s[8:9], v7, s16, v[16:17]
	v_or_b32_e32 v7, 56, v6
	v_mad_i64_i32 v[52:53], s[8:9], v7, s16, v[16:17]
	v_add_u32_e32 v7, 58, v6
	v_mad_i64_i32 v[54:55], s[8:9], v7, s16, v[16:17]
	v_or_b32_e32 v7, 60, v6
	v_mad_i64_i32 v[56:57], s[8:9], v7, s16, v[16:17]
	v_add_u32_e32 v7, 62, v6
	v_mad_i64_i32 v[58:59], s[8:9], v7, s16, v[16:17]
	global_load_dword v21, v[18:19], off nt
	s_nop 0
	global_load_dword v23, v[22:23], off nt
	s_nop 0
	global_load_dword v22, v[48:49], off nt
	global_load_dword v20, v[50:51], off nt
	global_load_dword v17, v[52:53], off nt
	global_load_dword v19, v[54:55], off nt
	global_load_dword v18, v[56:57], off nt
	global_load_dword v16, v[58:59], off nt
	v_ashrrev_i32_e32 v7, 31, v6
	s_and_b64 vcc, exec, s[0:1]
	v_lshl_add_u64 v[6:7], v[6:7], 2, s[54:55]
	s_cbranch_vccnz .LBB0_62
	global_load_dword v100, v[6:7], off
	global_load_dword v101, v[6:7], off offset:8
	global_load_dword v102, v[6:7], off offset:16
	global_load_dword v103, v[6:7], off offset:24
	global_load_dword v104, v[6:7], off offset:32
	global_load_dword v105, v[6:7], off offset:40
	global_load_dword v106, v[6:7], off offset:48
	global_load_dword v107, v[6:7], off offset:56
	global_load_dword v108, v[6:7], off offset:64
	global_load_dword v109, v[6:7], off offset:72
	global_load_dword v110, v[6:7], off offset:80
	global_load_dword v111, v[6:7], off offset:88
	global_load_dword v112, v[6:7], off offset:96
	global_load_dword v113, v[6:7], off offset:104
	global_load_dword v114, v[6:7], off offset:112
	global_load_dword v115, v[6:7], off offset:120
	global_load_dword v116, v[6:7], off offset:128
	global_load_dword v117, v[6:7], off offset:136
	global_load_dword v118, v[6:7], off offset:144
	global_load_dword v119, v[6:7], off offset:152
	global_load_dword v120, v[6:7], off offset:160
	global_load_dword v121, v[6:7], off offset:168
	global_load_dword v122, v[6:7], off offset:176
	global_load_dword v123, v[6:7], off offset:184
	global_load_dword v124, v[6:7], off offset:192
	global_load_dword v125, v[6:7], off offset:200
	global_load_dword v126, v[6:7], off offset:208
	global_load_dword v127, v[6:7], off offset:216
	global_load_dword v128, v[6:7], off offset:224
	global_load_dword v129, v[6:7], off offset:232
	global_load_dword v130, v[6:7], off offset:240
	global_load_dword v131, v[6:7], off offset:248
	s_waitcnt vmcnt(0)
	v_mov_b32_e32 v49, v100
	v_mov_b32_e32 v50, v101
	v_mov_b32_e32 v51, v102
	v_mov_b32_e32 v48, v103
	s_waitcnt vmcnt(3)
	v_mul_f32_e32 v52, v45, v49
	s_waitcnt vmcnt(2)
	v_mul_f32_e32 v50, v47, v50
	s_waitcnt vmcnt(1)
	v_mul_f32_e32 v49, v46, v51
	ds_write2_b32 v11, v52, v50 offset1:66
	s_cbranch_execnz .LBB0_42

.LBB0_42:
	s_waitcnt vmcnt(0)
	v_mul_f32_e32 v44, v44, v48
	s_and_b64 vcc, exec, s[0:1]
	ds_write2_b32 v12, v49, v44 offset1:66
	s_cbranch_vccnz .LBB0_63
	v_mov_b32_e32 v45, v104
	v_mov_b32_e32 v46, v105
	v_mov_b32_e32 v47, v106
	v_mov_b32_e32 v44, v107
	s_waitcnt vmcnt(3)
	v_mul_f32_e32 v48, v41, v45
	s_waitcnt vmcnt(2)
	v_mul_f32_e32 v46, v43, v46
	s_waitcnt vmcnt(1)
	v_mul_f32_e32 v45, v42, v47
	ds_write2_b32 v13, v48, v46 offset1:66
	s_cbranch_execnz .LBB0_45

.LBB0_45:
	s_waitcnt vmcnt(0)
	v_mul_f32_e32 v40, v40, v44
	s_and_b64 vcc, exec, s[0:1]
	ds_write2_b32 v14, v45, v40 offset1:66
	s_cbranch_vccnz .LBB0_64
	v_mov_b32_e32 v41, v108
	v_mov_b32_e32 v42, v109
	v_mov_b32_e32 v43, v110
	v_mov_b32_e32 v40, v111
	s_waitcnt vmcnt(3)
	v_mul_f32_e32 v44, v37, v41
	s_waitcnt vmcnt(2)
	v_mul_f32_e32 v42, v39, v42
	s_waitcnt vmcnt(1)
	v_mul_f32_e32 v41, v38, v43
	ds_write2_b32 v15, v44, v42 offset1:66
	s_cbranch_execnz .LBB0_48

.LBB0_74:
	s_ashr_i32 s4, s8, 31
	s_lshr_b32 s4, s4, 25
	s_add_i32 s4, s8, s4
	s_ashr_i32 s5, s4, 7
	s_lshl_b32 s4, s5, 6
	s_lshl_b32 s5, s5, 12
	s_sub_i32 s6, s9, s5
	v_or_b32_e32 v6, s4, v8
	s_ashr_i32 s7, s6, 31
	v_ashrrev_i32_e32 v7, 31, v6
	v_lshl_add_u64 v[16:17], s[6:7], 2, v[2:3]
	v_lshlrev_b64 v[18:19], 14, v[6:7]
	v_lshl_add_u64 v[22:23], v[16:17], 0, v[18:19]
	v_add_co_u32_e32 v20, vcc, s11, v22
	v_or_b32_e32 v24, 0x10000, v18
	s_nop 0
	v_addc_co_u32_e32 v21, vcc, 0, v23, vcc
	v_add_co_u32_e32 v26, vcc, s15, v22
	v_mov_b32_e32 v25, v19
	s_nop 0
	v_addc_co_u32_e32 v27, vcc, 0, v23, vcc
	v_add_co_u32_e32 v30, vcc, s16, v22
	v_lshl_add_u64 v[24:25], v[16:17], 0, v[24:25]
	s_nop 0
	v_addc_co_u32_e32 v31, vcc, 0, v23, vcc
	v_add_co_u32_e32 v34, vcc, s17, v22
	v_or_b32_e32 v28, 0x20000, v18
	v_mov_b32_e32 v29, v19
	v_or_b32_e32 v32, 0x30000, v18
	v_mov_b32_e32 v33, v19
	v_addc_co_u32_e32 v35, vcc, 0, v23, vcc
	v_lshl_add_u64 v[28:29], v[16:17], 0, v[28:29]
	v_lshl_add_u64 v[32:33], v[16:17], 0, v[32:33]
	global_load_dword v45, v[22:23], off nt
	global_load_dword v47, v[20:21], off nt
	global_load_dword v46, v[24:25], off nt
	global_load_dword v44, v[26:27], off nt
	global_load_dword v41, v[28:29], off nt
	global_load_dword v43, v[30:31], off nt
	global_load_dword v42, v[32:33], off nt
	global_load_dword v40, v[34:35], off nt
	v_add_co_u32_e32 v24, vcc, s18, v22
	v_or_b32_e32 v20, 0x40000, v18
	s_nop 0
	v_addc_co_u32_e32 v25, vcc, 0, v23, vcc
	v_add_co_u32_e32 v28, vcc, s19, v22
	v_mov_b32_e32 v21, v19
	s_nop 0
	v_addc_co_u32_e32 v29, vcc, 0, v23, vcc
	v_add_co_u32_e32 v34, vcc, s20, v22
	v_lshl_add_u64 v[20:21], v[16:17], 0, v[20:21]
	s_nop 0
	v_addc_co_u32_e32 v35, vcc, 0, v23, vcc
	v_add_co_u32_e32 v50, vcc, s21, v22
	v_or_b32_e32 v26, 0x50000, v18
	v_mov_b32_e32 v27, v19
	v_or_b32_e32 v30, 0x60000, v18
	v_mov_b32_e32 v31, v19
	v_or_b32_e32 v32, 0x70000, v18
	v_mov_b32_e32 v33, v19
	v_addc_co_u32_e32 v51, vcc, 0, v23, vcc
	v_lshl_add_u64 v[26:27], v[16:17], 0, v[26:27]
	v_lshl_add_u64 v[30:31], v[16:17], 0, v[30:31]
	v_lshl_add_u64 v[48:49], v[16:17], 0, v[32:33]
	global_load_dword v37, v[20:21], off nt
	global_load_dword v39, v[24:25], off nt
	global_load_dword v38, v[26:27], off nt
	global_load_dword v36, v[28:29], off nt
	global_load_dword v33, v[30:31], off nt
	s_nop 0
	global_load_dword v35, v[34:35], off nt
	s_nop 0
	global_load_dword v34, v[48:49], off nt
	global_load_dword v32, v[50:51], off nt
	v_add_co_u32_e32 v24, vcc, s22, v22
	v_or_b32_e32 v20, 0x80000, v18
	s_nop 0
	v_addc_co_u32_e32 v25, vcc, 0, v23, vcc
	v_add_co_u32_e32 v48, vcc, s23, v22
	v_mov_b32_e32 v21, v19
	s_nop 0
	v_addc_co_u32_e32 v49, vcc, 0, v23, vcc
	v_add_co_u32_e32 v52, vcc, s24, v22
	v_or_b32_e32 v26, 0x90000, v18
	s_nop 0
	v_addc_co_u32_e32 v53, vcc, 0, v23, vcc
	v_mov_b32_e32 v27, v19
	v_or_b32_e32 v28, 0xa0000, v18
	v_mov_b32_e32 v29, v19
	v_add_co_u32_e32 v56, vcc, s25, v22
	v_lshl_add_u64 v[20:21], v[16:17], 0, v[20:21]
	v_lshl_add_u64 v[26:27], v[16:17], 0, v[26:27]
	v_lshl_add_u64 v[50:51], v[16:17], 0, v[28:29]
	v_or_b32_e32 v28, 0xb0000, v18
	v_addc_co_u32_e32 v57, vcc, 0, v23, vcc
	v_lshl_add_u64 v[54:55], v[16:17], 0, v[28:29]
	global_load_dword v29, v[20:21], off nt
	global_load_dword v31, v[24:25], off nt
	global_load_dword v30, v[26:27], off nt
	global_load_dword v28, v[48:49], off nt
	s_nop 0
	global_load_dword v24, v[50:51], off nt
	global_load_dword v27, v[52:53], off nt
	global_load_dword v25, v[54:55], off nt
	global_load_dword v21, v[56:57], off nt
	v_add_co_u32_e32 v50, vcc, s26, v22
	v_or_b32_e32 v48, 0xc0000, v18
	s_nop 0
	v_addc_co_u32_e32 v51, vcc, 0, v23, vcc
	v_add_co_u32_e32 v54, vcc, s27, v22
	v_mov_b32_e32 v49, v19
	s_nop 0
	v_addc_co_u32_e32 v55, vcc, 0, v23, vcc
	v_add_co_u32_e32 v58, vcc, 0xe8000, v22
	v_lshl_add_u64 v[48:49], v[16:17], 0, v[48:49]
	s_nop 0
	v_addc_co_u32_e32 v59, vcc, 0, v23, vcc
	v_or_b32_e32 v52, 0xd0000, v18
	v_mov_b32_e32 v53, v19
	v_or_b32_e32 v56, 0xe0000, v18
	v_mov_b32_e32 v57, v19
	v_or_b32_e32 v18, 0xf0000, v18
	v_add_co_u32_e32 v62, vcc, 0xf8000, v22
	v_lshl_add_u64 v[52:53], v[16:17], 0, v[52:53]
	v_lshl_add_u64 v[56:57], v[16:17], 0, v[56:57]
	v_lshl_add_u64 v[60:61], v[16:17], 0, v[18:19]
	v_addc_co_u32_e32 v63, vcc, 0, v23, vcc
	global_load_dword v22, v[48:49], off nt
	global_load_dword v26, v[50:51], off nt
	global_load_dword v23, v[52:53], off nt
	global_load_dword v20, v[54:55], off nt
	global_load_dword v17, v[56:57], off nt
	global_load_dword v19, v[58:59], off nt
	global_load_dword v18, v[60:61], off nt
	global_load_dword v16, v[62:63], off nt
	s_and_b64 vcc, exec, s[0:1]
	v_lshl_add_u64 v[6:7], v[6:7], 2, s[58:59]
	s_cbranch_vccnz .LBB0_97
	global_load_dword v100, v[6:7], off
	global_load_dword v101, v[6:7], off offset:8
	global_load_dword v102, v[6:7], off offset:16
	global_load_dword v103, v[6:7], off offset:24
	global_load_dword v104, v[6:7], off offset:32
	global_load_dword v105, v[6:7], off offset:40
	global_load_dword v106, v[6:7], off offset:48
	global_load_dword v107, v[6:7], off offset:56
	global_load_dword v108, v[6:7], off offset:64
	global_load_dword v109, v[6:7], off offset:72
	global_load_dword v110, v[6:7], off offset:80
	global_load_dword v111, v[6:7], off offset:88
	global_load_dword v112, v[6:7], off offset:96
	global_load_dword v113, v[6:7], off offset:104
	global_load_dword v114, v[6:7], off offset:112
	global_load_dword v115, v[6:7], off offset:120
	global_load_dword v116, v[6:7], off offset:128
	global_load_dword v117, v[6:7], off offset:136
	global_load_dword v118, v[6:7], off offset:144
	global_load_dword v119, v[6:7], off offset:152
	global_load_dword v120, v[6:7], off offset:160
	global_load_dword v121, v[6:7], off offset:168
	global_load_dword v122, v[6:7], off offset:176
	global_load_dword v123, v[6:7], off offset:184
	global_load_dword v124, v[6:7], off offset:192
	global_load_dword v125, v[6:7], off offset:200
	global_load_dword v126, v[6:7], off offset:208
	global_load_dword v127, v[6:7], off offset:216
	global_load_dword v128, v[6:7], off offset:224
	global_load_dword v129, v[6:7], off offset:232
	global_load_dword v130, v[6:7], off offset:240
	global_load_dword v131, v[6:7], off offset:248
	s_waitcnt vmcnt(0)
	v_mov_b32_e32 v49, v100
	v_mov_b32_e32 v50, v101
	v_mov_b32_e32 v51, v102
	v_mov_b32_e32 v48, v103
	s_waitcnt vmcnt(3)
	v_mul_f32_e32 v52, v45, v49
	s_waitcnt vmcnt(2)
	v_mul_f32_e32 v50, v47, v50
	s_waitcnt vmcnt(1)
	v_mul_f32_e32 v49, v46, v51
	ds_write2_b32 v13, v52, v50 offset1:66
	s_cbranch_execnz .LBB0_77

.LBB0_77:
	s_waitcnt vmcnt(0)
	v_mul_f32_e32 v44, v44, v48
	s_and_b64 vcc, exec, s[0:1]
	ds_write2_b32 v11, v49, v44 offset1:66
	s_cbranch_vccnz .LBB0_98
	v_mov_b32_e32 v45, v104
	v_mov_b32_e32 v46, v105
	v_mov_b32_e32 v47, v106
	v_mov_b32_e32 v44, v107
	s_waitcnt vmcnt(3)
	v_mul_f32_e32 v48, v41, v45
	s_waitcnt vmcnt(2)
	v_mul_f32_e32 v46, v43, v46
	s_waitcnt vmcnt(1)
	v_mul_f32_e32 v45, v42, v47
	ds_write2_b32 v14, v48, v46 offset1:66
	s_cbranch_execnz .LBB0_80

.LBB0_80:
	s_waitcnt vmcnt(0)
	v_mul_f32_e32 v40, v40, v44
	s_and_b64 vcc, exec, s[0:1]
	ds_write2_b32 v12, v45, v40 offset1:66
	s_cbranch_vccnz .LBB0_99
	v_mov_b32_e32 v41, v108
	v_mov_b32_e32 v42, v109
	v_mov_b32_e32 v43, v110
	v_mov_b32_e32 v40, v111
	s_waitcnt vmcnt(3)
	v_mul_f32_e32 v44, v37, v41
	s_waitcnt vmcnt(2)
	v_mul_f32_e32 v42, v39, v42
	s_waitcnt vmcnt(1)
	v_mul_f32_e32 v41, v38, v43
	ds_write2_b32 v15, v44, v42 offset1:66
	s_cbranch_execnz .LBB0_83

.LBB0_89:
	s_waitcnt vmcnt(0)
	v_mul_f32_e32 v28, v28, v33
	ds_write2_b32 v32, v34, v28 offset0:148 offset1:214
	s_and_b64 vcc, exec, s[0:1]
	v_add_u32_e32 v28, 0xc00, v15
	s_cbranch_vccnz .LBB0_102
	v_mov_b32_e32 v30, v120
	v_mov_b32_e32 v31, v121
	v_mov_b32_e32 v32, v122
	v_mov_b32_e32 v29, v123
	s_waitcnt vmcnt(3)
	v_mul_f32_e32 v33, v24, v30
	s_waitcnt vmcnt(2)
	v_mul_f32_e32 v31, v27, v31
	s_waitcnt vmcnt(1)
	v_mul_f32_e32 v30, v25, v32
	ds_write2_b32 v28, v33, v31 offset0:24 offset1:90
	s_cbranch_execnz .LBB0_92

.LBB0_92:
	s_waitcnt vmcnt(0)
	v_mul_f32_e32 v21, v21, v29
	ds_write2_b32 v28, v30, v21 offset0:156 offset1:222
	s_and_b64 vcc, exec, s[0:1]
	v_add_u32_e32 v21, 0x1000, v15
	s_cbranch_vccnz .LBB0_103
	v_mov_b32_e32 v25, v124
	v_mov_b32_e32 v27, v125
	v_mov_b32_e32 v28, v126
	v_mov_b32_e32 v24, v127
	s_waitcnt vmcnt(3)
	v_mul_f32_e32 v29, v22, v25
	s_waitcnt vmcnt(2)
	v_mul_f32_e32 v27, v26, v27
	s_waitcnt vmcnt(1)
	v_mul_f32_e32 v25, v23, v28
	ds_write2_b32 v21, v29, v27 offset0:32 offset1:98
	s_cbranch_execnz .LBB0_95

.LBB0_95:
	s_waitcnt vmcnt(0)
	v_mul_f32_e32 v20, v20, v24
	ds_write2_b32 v21, v25, v20 offset0:164 offset1:230
	s_and_b64 vcc, exec, s[0:1]
	v_add_u32_e32 v20, 0x1400, v15
	s_cbranch_vccnz .LBB0_104
	v_mov_b32_e32 v21, v128
	v_mov_b32_e32 v22, v129
	v_mov_b32_e32 v23, v130
	s_nop 0
	v_mov_b32_e32 v6, v131
	s_waitcnt vmcnt(3)
	v_mul_f32_e32 v21, v17, v21
	s_waitcnt vmcnt(2)
	v_mul_f32_e32 v22, v19, v22
	s_waitcnt vmcnt(1)
	v_mul_f32_e32 v7, v18, v23
	ds_write2_b32 v20, v21, v22 offset0:40 offset1:106
	s_cbranch_execnz .LBB0_73
	s_branch .LBB0_105

.LBB0_112:
	s_mul_hi_i32 s6, s15, 0x2aaaaaab
	s_lshr_b32 s7, s6, 31
	s_ashr_i32 s6, s6, 6
	s_add_i32 s7, s6, s7
	s_lshl_b32 s6, s7, 6
	s_mulk_i32 s7, 0xd000
	s_add_i32 s8, s16, s7
	v_or_b32_e32 v6, s6, v8
	s_ashr_i32 s9, s8, 31
	v_lshl_add_u64 v[16:17], s[8:9], 2, v[2:3]
	v_add_u32_e32 v7, 2, v6
	v_mad_i64_i32 v[20:21], s[10:11], v7, s18, v[16:17]
	v_or_b32_e32 v7, 4, v6
	v_mad_i64_i32 v[22:23], s[10:11], v7, s18, v[16:17]
	v_add_u32_e32 v7, 6, v6
	v_mad_i64_i32 v[24:25], s[10:11], v7, s18, v[16:17]
	v_or_b32_e32 v7, 8, v6
	v_mad_i64_i32 v[26:27], s[10:11], v7, s18, v[16:17]
	v_add_u32_e32 v7, 10, v6
	v_mad_i64_i32 v[28:29], s[10:11], v7, s18, v[16:17]
	v_or_b32_e32 v7, 12, v6
	v_mad_i64_i32 v[30:31], s[10:11], v7, s18, v[16:17]
	v_add_u32_e32 v7, 14, v6
	v_mad_i64_i32 v[18:19], s[10:11], v6, s18, v[16:17]
	v_mad_i64_i32 v[32:33], s[10:11], v7, s18, v[16:17]
	v_or_b32_e32 v7, 16, v6
	global_load_dword v45, v[18:19], off nt
	global_load_dword v47, v[20:21], off nt
	global_load_dword v46, v[22:23], off nt
	global_load_dword v44, v[24:25], off nt
	global_load_dword v41, v[26:27], off nt
	global_load_dword v43, v[28:29], off nt
	global_load_dword v42, v[30:31], off nt
	global_load_dword v40, v[32:33], off nt
	v_mad_i64_i32 v[18:19], s[10:11], v7, s18, v[16:17]
	v_add_u32_e32 v7, 18, v6
	v_mad_i64_i32 v[20:21], s[10:11], v7, s18, v[16:17]
	v_or_b32_e32 v7, 20, v6
	v_mad_i64_i32 v[22:23], s[10:11], v7, s18, v[16:17]
	v_add_u32_e32 v7, 22, v6
	v_mad_i64_i32 v[24:25], s[10:11], v7, s18, v[16:17]
	v_or_b32_e32 v7, 24, v6
	v_mad_i64_i32 v[26:27], s[10:11], v7, s18, v[16:17]
	v_add_u32_e32 v7, 26, v6
	v_mad_i64_i32 v[28:29], s[10:11], v7, s18, v[16:17]
	v_or_b32_e32 v7, 28, v6
	v_mad_i64_i32 v[30:31], s[10:11], v7, s18, v[16:17]
	v_add_u32_e32 v7, 30, v6
	v_mad_i64_i32 v[48:49], s[10:11], v7, s18, v[16:17]
	v_or_b32_e32 v7, 32, v6
	global_load_dword v37, v[18:19], off nt
	global_load_dword v39, v[20:21], off nt
	global_load_dword v38, v[22:23], off nt
	global_load_dword v36, v[24:25], off nt
	global_load_dword v33, v[26:27], off nt
	global_load_dword v35, v[28:29], off nt
	global_load_dword v34, v[30:31], off nt
	global_load_dword v32, v[48:49], off nt
	v_mad_i64_i32 v[18:19], s[10:11], v7, s18, v[16:17]
	v_add_u32_e32 v7, 34, v6
	v_mad_i64_i32 v[20:21], s[10:11], v7, s18, v[16:17]
	v_or_b32_e32 v7, 36, v6
	v_mad_i64_i32 v[22:23], s[10:11], v7, s18, v[16:17]
	v_add_u32_e32 v7, 38, v6
	v_mad_i64_i32 v[48:49], s[10:11], v7, s18, v[16:17]
	v_or_b32_e32 v7, 40, v6
	v_mad_i64_i32 v[50:51], s[10:11], v7, s18, v[16:17]
	v_add_u32_e32 v7, 42, v6
	v_mad_i64_i32 v[52:53], s[10:11], v7, s18, v[16:17]
	v_or_b32_e32 v7, 44, v6
	v_mad_i64_i32 v[54:55], s[10:11], v7, s18, v[16:17]
	v_add_u32_e32 v7, 46, v6
	v_mad_i64_i32 v[56:57], s[10:11], v7, s18, v[16:17]
	v_or_b32_e32 v7, 48, v6
	global_load_dword v29, v[18:19], off nt
	global_load_dword v31, v[20:21], off nt
	global_load_dword v30, v[22:23], off nt
	global_load_dword v28, v[48:49], off nt
	global_load_dword v25, v[50:51], off nt
	global_load_dword v27, v[52:53], off nt
	global_load_dword v26, v[54:55], off nt
	global_load_dword v24, v[56:57], off nt
	v_mad_i64_i32 v[48:49], s[10:11], v7, s18, v[16:17]
	v_add_u32_e32 v7, 50, v6
	v_mad_i64_i32 v[50:51], s[10:11], v7, s18, v[16:17]
	v_or_b32_e32 v7, 52, v6
	v_mad_i64_i32 v[52:53], s[10:11], v7, s18, v[16:17]
	v_add_u32_e32 v7, 54, v6
	v_mad_i64_i32 v[54:55], s[10:11], v7, s18, v[16:17]
	v_or_b32_e32 v7, 56, v6
	v_mad_i64_i32 v[56:57], s[10:11], v7, s18, v[16:17]
	v_add_u32_e32 v7, 58, v6
	v_mad_i64_i32 v[58:59], s[10:11], v7, s18, v[16:17]
	v_or_b32_e32 v7, 60, v6
	v_mad_i64_i32 v[60:61], s[10:11], v7, s18, v[16:17]
	v_add_u32_e32 v7, 62, v6
	v_mad_i64_i32 v[62:63], s[10:11], v7, s18, v[16:17]
	global_load_dword v21, v[48:49], off nt
	global_load_dword v23, v[50:51], off nt
	global_load_dword v22, v[52:53], off nt
	global_load_dword v20, v[54:55], off nt
	global_load_dword v17, v[56:57], off nt
	global_load_dword v19, v[58:59], off nt
	global_load_dword v18, v[60:61], off nt
	global_load_dword v16, v[62:63], off nt
	v_ashrrev_i32_e32 v7, 31, v6
	s_and_b64 vcc, exec, s[0:1]
	v_lshl_add_u64 v[6:7], v[6:7], 2, s[80:81]
	s_cbranch_vccnz .LBB0_135
	global_load_dword v100, v[6:7], off
	global_load_dword v101, v[6:7], off offset:8
	global_load_dword v102, v[6:7], off offset:16
	global_load_dword v103, v[6:7], off offset:24
	global_load_dword v104, v[6:7], off offset:32
	global_load_dword v105, v[6:7], off offset:40
	global_load_dword v106, v[6:7], off offset:48
	global_load_dword v107, v[6:7], off offset:56
	global_load_dword v108, v[6:7], off offset:64
	global_load_dword v109, v[6:7], off offset:72
	global_load_dword v110, v[6:7], off offset:80
	global_load_dword v111, v[6:7], off offset:88
	global_load_dword v112, v[6:7], off offset:96
	global_load_dword v113, v[6:7], off offset:104
	global_load_dword v114, v[6:7], off offset:112
	global_load_dword v115, v[6:7], off offset:120
	global_load_dword v116, v[6:7], off offset:128
	global_load_dword v117, v[6:7], off offset:136
	global_load_dword v118, v[6:7], off offset:144
	global_load_dword v119, v[6:7], off offset:152
	global_load_dword v120, v[6:7], off offset:160
	global_load_dword v121, v[6:7], off offset:168
	global_load_dword v122, v[6:7], off offset:176
	global_load_dword v123, v[6:7], off offset:184
	global_load_dword v124, v[6:7], off offset:192
	global_load_dword v125, v[6:7], off offset:200
	global_load_dword v126, v[6:7], off offset:208
	global_load_dword v127, v[6:7], off offset:216
	global_load_dword v128, v[6:7], off offset:224
	global_load_dword v129, v[6:7], off offset:232
	global_load_dword v130, v[6:7], off offset:240
	global_load_dword v131, v[6:7], off offset:248
	s_waitcnt vmcnt(0)
	v_mov_b32_e32 v49, v100
	v_mov_b32_e32 v50, v101
	v_mov_b32_e32 v51, v102
	v_mov_b32_e32 v48, v103
	s_waitcnt vmcnt(3)
	v_mul_f32_e32 v52, v45, v49
	s_waitcnt vmcnt(2)
	v_mul_f32_e32 v50, v47, v50
	s_waitcnt vmcnt(1)
	v_mul_f32_e32 v49, v46, v51
	ds_write2_b32 v11, v52, v50 offset1:66
	s_cbranch_execnz .LBB0_115

.LBB0_133:
	s_waitcnt vmcnt(0)
	v_mul_f32_e32 v20, v20, v25
	ds_write2_b32 v24, v26, v20 offset0:164 offset1:230
	s_and_b64 vcc, exec, s[0:1]
	v_add_u32_e32 v20, 0x1400, v15
	s_cbranch_vccnz .LBB0_142
	v_mov_b32_e32 v22, v128
	v_mov_b32_e32 v23, v129
	v_mov_b32_e32 v24, v130
	v_mov_b32_e32 v21, v131
	s_waitcnt vmcnt(3)
	v_mul_f32_e32 v7, v17, v22
	s_waitcnt vmcnt(2)
	v_mul_f32_e32 v22, v19, v23
	s_waitcnt vmcnt(1)
	v_mul_f32_e32 v6, v18, v24
	ds_write2_b32 v20, v7, v22 offset0:40 offset1:106
	s_cbranch_execnz .LBB0_111
	s_branch .LBB0_143

.LBB0_147:
	s_ashr_i32 s0, s15, 31
	s_lshr_b32 s0, s0, 24
	s_add_i32 s0, s15, s0
	s_ashr_i32 s5, s0, 8
	s_lshl_b32 s4, s5, 6
	s_lshl_b32 s0, s5, 13
	s_sub_i32 s8, s16, s0
	v_or_b32_e32 v6, s4, v8
	s_ashr_i32 s9, s8, 31
	v_ashrrev_i32_e32 v7, 31, v6
	v_lshl_add_u64 v[16:17], s[8:9], 2, v[2:3]
	v_lshlrev_b64 v[18:19], 15, v[6:7]
	v_lshl_add_u64 v[22:23], v[16:17], 0, v[18:19]
	v_add_co_u32_e32 v20, vcc, s18, v22
	v_or_b32_e32 v24, 0x20000, v18
	s_nop 0
	v_addc_co_u32_e32 v21, vcc, 0, v23, vcc
	v_add_co_u32_e32 v26, vcc, s19, v22
	v_mov_b32_e32 v25, v19
	s_nop 0
	v_addc_co_u32_e32 v27, vcc, 0, v23, vcc
	v_add_co_u32_e32 v30, vcc, s20, v22
	v_lshl_add_u64 v[24:25], v[16:17], 0, v[24:25]
	s_nop 0
	v_addc_co_u32_e32 v31, vcc, 0, v23, vcc
	v_add_co_u32_e32 v34, vcc, s21, v22
	v_or_b32_e32 v28, 0x40000, v18
	v_mov_b32_e32 v29, v19
	v_or_b32_e32 v32, 0x60000, v18
	v_mov_b32_e32 v33, v19
	v_addc_co_u32_e32 v35, vcc, 0, v23, vcc
	v_lshl_add_u64 v[28:29], v[16:17], 0, v[28:29]
	v_lshl_add_u64 v[32:33], v[16:17], 0, v[32:33]
	global_load_dword v45, v[22:23], off nt
	global_load_dword v47, v[20:21], off nt
	global_load_dword v46, v[24:25], off nt
	global_load_dword v44, v[26:27], off nt
	global_load_dword v41, v[28:29], off nt
	global_load_dword v43, v[30:31], off nt
	global_load_dword v42, v[32:33], off nt
	global_load_dword v40, v[34:35], off nt
	v_add_co_u32_e32 v24, vcc, s22, v22
	v_or_b32_e32 v20, 0x80000, v18
	s_nop 0
	v_addc_co_u32_e32 v25, vcc, 0, v23, vcc
	v_add_co_u32_e32 v28, vcc, s23, v22
	v_mov_b32_e32 v21, v19
	s_nop 0
	v_addc_co_u32_e32 v29, vcc, 0, v23, vcc
	v_add_co_u32_e32 v34, vcc, s24, v22
	v_lshl_add_u64 v[20:21], v[16:17], 0, v[20:21]
	s_nop 0
	v_addc_co_u32_e32 v35, vcc, 0, v23, vcc
	v_add_co_u32_e32 v50, vcc, s25, v22
	v_or_b32_e32 v26, 0xa0000, v18
	v_mov_b32_e32 v27, v19
	v_or_b32_e32 v30, 0xc0000, v18
	v_mov_b32_e32 v31, v19
	v_or_b32_e32 v32, 0xe0000, v18
	v_mov_b32_e32 v33, v19
	v_addc_co_u32_e32 v51, vcc, 0, v23, vcc
	v_lshl_add_u64 v[26:27], v[16:17], 0, v[26:27]
	v_lshl_add_u64 v[30:31], v[16:17], 0, v[30:31]
	v_lshl_add_u64 v[48:49], v[16:17], 0, v[32:33]
	global_load_dword v37, v[20:21], off nt
	global_load_dword v39, v[24:25], off nt
	global_load_dword v38, v[26:27], off nt
	global_load_dword v36, v[28:29], off nt
	global_load_dword v33, v[30:31], off nt
	s_nop 0
	global_load_dword v35, v[34:35], off nt
	s_nop 0
	global_load_dword v34, v[48:49], off nt
	global_load_dword v32, v[50:51], off nt
	v_add_co_u32_e32 v24, vcc, s26, v22
	v_or_b32_e32 v20, 0x100000, v18
	s_nop 0
	v_addc_co_u32_e32 v25, vcc, 0, v23, vcc
	v_add_co_u32_e32 v48, vcc, s27, v22
	v_mov_b32_e32 v21, v19
	s_nop 0
	v_addc_co_u32_e32 v49, vcc, 0, v23, vcc
	v_add_co_u32_e32 v52, vcc, s28, v22
	v_or_b32_e32 v26, 0x120000, v18
	s_nop 0
	v_addc_co_u32_e32 v53, vcc, 0, v23, vcc
	v_mov_b32_e32 v27, v19
	v_or_b32_e32 v28, 0x140000, v18
	v_mov_b32_e32 v29, v19
	v_add_co_u32_e32 v56, vcc, s29, v22
	v_lshl_add_u64 v[20:21], v[16:17], 0, v[20:21]
	v_lshl_add_u64 v[26:27], v[16:17], 0, v[26:27]
	v_lshl_add_u64 v[50:51], v[16:17], 0, v[28:29]
	v_or_b32_e32 v28, 0x160000, v18
	v_addc_co_u32_e32 v57, vcc, 0, v23, vcc
	v_lshl_add_u64 v[54:55], v[16:17], 0, v[28:29]
	global_load_dword v29, v[20:21], off nt
	global_load_dword v31, v[24:25], off nt
	global_load_dword v30, v[26:27], off nt
	global_load_dword v28, v[48:49], off nt
	s_nop 0
	global_load_dword v24, v[50:51], off nt
	global_load_dword v27, v[52:53], off nt
	global_load_dword v25, v[54:55], off nt
	global_load_dword v21, v[56:57], off nt
	v_add_co_u32_e32 v50, vcc, s30, v22
	v_or_b32_e32 v48, 0x180000, v18
	s_nop 0
	v_addc_co_u32_e32 v51, vcc, 0, v23, vcc
	v_add_co_u32_e32 v54, vcc, s31, v22
	v_mov_b32_e32 v49, v19
	s_nop 0
	v_addc_co_u32_e32 v55, vcc, 0, v23, vcc
	v_add_co_u32_e32 v58, vcc, 0x1d0000, v22
	v_lshl_add_u64 v[48:49], v[16:17], 0, v[48:49]
	s_nop 0
	v_addc_co_u32_e32 v59, vcc, 0, v23, vcc
	v_or_b32_e32 v52, 0x1a0000, v18
	v_mov_b32_e32 v53, v19
	v_or_b32_e32 v56, 0x1c0000, v18
	v_mov_b32_e32 v57, v19
	v_or_b32_e32 v18, 0x1e0000, v18
	v_add_co_u32_e32 v62, vcc, 0x1f0000, v22
	v_lshl_add_u64 v[52:53], v[16:17], 0, v[52:53]
	v_lshl_add_u64 v[56:57], v[16:17], 0, v[56:57]
	v_lshl_add_u64 v[60:61], v[16:17], 0, v[18:19]
	v_addc_co_u32_e32 v63, vcc, 0, v23, vcc
	global_load_dword v22, v[48:49], off nt
	global_load_dword v26, v[50:51], off nt
	global_load_dword v23, v[52:53], off nt
	global_load_dword v20, v[54:55], off nt
	global_load_dword v17, v[56:57], off nt
	global_load_dword v19, v[58:59], off nt
	global_load_dword v18, v[60:61], off nt
	global_load_dword v16, v[62:63], off nt
	s_and_b64 vcc, exec, s[6:7]
	v_lshl_add_u64 v[6:7], v[6:7], 2, s[86:87]
	s_cbranch_vccz .LBB0_175
	global_load_dword v100, v[6:7], off
	global_load_dword v101, v[6:7], off offset:8
	global_load_dword v102, v[6:7], off offset:16
	global_load_dword v103, v[6:7], off offset:24
	global_load_dword v104, v[6:7], off offset:32
	global_load_dword v105, v[6:7], off offset:40
	global_load_dword v106, v[6:7], off offset:48
	global_load_dword v107, v[6:7], off offset:56
	global_load_dword v108, v[6:7], off offset:64
	global_load_dword v109, v[6:7], off offset:72
	global_load_dword v110, v[6:7], off offset:80
	global_load_dword v111, v[6:7], off offset:88
	global_load_dword v112, v[6:7], off offset:96
	global_load_dword v113, v[6:7], off offset:104
	global_load_dword v114, v[6:7], off offset:112
	global_load_dword v115, v[6:7], off offset:120
	global_load_dword v116, v[6:7], off offset:128
	global_load_dword v117, v[6:7], off offset:136
	global_load_dword v118, v[6:7], off offset:144
	global_load_dword v119, v[6:7], off offset:152
	global_load_dword v120, v[6:7], off offset:160
	global_load_dword v121, v[6:7], off offset:168
	global_load_dword v122, v[6:7], off offset:176
	global_load_dword v123, v[6:7], off offset:184
	global_load_dword v124, v[6:7], off offset:192
	global_load_dword v125, v[6:7], off offset:200
	global_load_dword v126, v[6:7], off offset:208
	global_load_dword v127, v[6:7], off offset:216
	global_load_dword v128, v[6:7], off offset:224
	global_load_dword v129, v[6:7], off offset:232
	global_load_dword v130, v[6:7], off offset:240
	global_load_dword v131, v[6:7], off offset:248
	s_waitcnt vmcnt(0)
	v_mov_b32_e32 v48, v100
	v_mov_b32_e32 v50, v101
	v_mov_b32_e32 v51, v102
	v_mov_b32_e32 v49, v103
	s_waitcnt vmcnt(3)
	v_mul_f32_e32 v52, v45, v48
	s_waitcnt vmcnt(2)
	v_mul_f32_e32 v50, v47, v50
	s_waitcnt vmcnt(1)
	v_mul_f32_e32 v48, v46, v51
	ds_write2_b32 v13, v52, v50 offset1:66
	s_cbranch_execnz .LBB0_150

.LBB0_150:
	s_waitcnt vmcnt(31)
	v_cndmask_b32_e64 v45, 0, 1, s[6:7]
	s_waitcnt vmcnt(0)
	v_mul_f32_e32 v44, v44, v49
	v_cmp_ne_u32_e64 s[0:1], 1, v45
	s_andn2_b64 vcc, exec, s[6:7]
	ds_write2_b32 v11, v48, v44 offset1:66
	s_cbranch_vccnz .LBB0_176
	v_mov_b32_e32 v45, v104
	v_mov_b32_e32 v46, v105
	v_mov_b32_e32 v47, v106
	v_mov_b32_e32 v44, v107
	s_waitcnt vmcnt(3)
	v_mul_f32_e32 v48, v41, v45
	s_waitcnt vmcnt(2)
	v_mul_f32_e32 v46, v43, v46
	s_waitcnt vmcnt(1)
	v_mul_f32_e32 v45, v42, v47
	ds_write2_b32 v14, v48, v46 offset1:66
	s_cbranch_execnz .LBB0_153

.LBB0_168:
	s_waitcnt vmcnt(0)
	v_mul_f32_e32 v20, v20, v24
	ds_write2_b32 v21, v25, v20 offset0:164 offset1:230
	s_and_b64 vcc, exec, s[0:1]
	v_add_u32_e32 v20, 0x1400, v15
	s_cbranch_vccnz .LBB0_182
	v_mov_b32_e32 v21, v128
	v_mov_b32_e32 v22, v129
	v_mov_b32_e32 v23, v130
	s_nop 0
	v_mov_b32_e32 v6, v131
	s_waitcnt vmcnt(3)
	v_mul_f32_e32 v21, v17, v21
	s_waitcnt vmcnt(2)
	v_mul_f32_e32 v22, v19, v22
	s_waitcnt vmcnt(1)
	v_mul_f32_e32 v7, v18, v23
	ds_write2_b32 v20, v21, v22 offset0:40 offset1:106
	s_cbranch_execnz .LBB0_171
